# v30 plus attention moved from P2 interval into P3 interval (P2 keeps conv_fix only), removing the seam after attention
# baseline (speedup 1.0000x reference)
_Z8mega_fwd4Args:
	s_mov_b32 s101, 0
	s_mov_b32 s100, 0
	s_mov_b32 s99, 0
	s_mov_b32 s98, 0
	s_mov_b32 s96, s2
	v_readfirstlane_b32 s2, v0
	s_lshr_b32 s2, s2, 6
	v_mbcnt_lo_u32_b32 v3, -1, 0
	v_mbcnt_hi_u32_b32 v3, -1, v3
	s_load_dword s15, s[0:1], 0xf8
	s_load_dwordx2 s[94:95], s[0:1], 0xe0
	s_load_dwordx4 s[4:7], s[0:1], 0xe8
	s_load_dwordx8 s[68:75], s[0:1], 0xc0
	v_writelane_b32 v254, s2, 0
	s_add_u32 s2, s0, 0xf8
	s_addc_u32 s3, s1, 0
	s_waitcnt lgkmcnt(0)
	v_writelane_b32 v254, s4, 1
	s_mov_b32 s10, s96
	s_nop 0
	v_writelane_b32 v254, s5, 2
	v_writelane_b32 v254, s6, 3
	v_writelane_b32 v254, s7, 4
	v_writelane_b32 v254, s2, 5
	s_nop 1
	v_writelane_b32 v254, s3, 6
	s_and_b32 s3, s15, 7
	s_mov_b32 s2, 0
	s_cmp_lg_u32 s3, 0
	s_cbranch_scc1 .LBB0_2
	s_ashr_i32 s4, s96, 31
	s_lshr_b32 s4, s4, 29
	s_add_i32 s4, s96, s4
	s_and_b32 s5, s4, -8
	s_ashr_i32 s3, s15, 3
	s_sub_i32 s5, s96, s5
	s_mul_i32 s3, s3, s5
	s_ashr_i32 s4, s4, 3
	s_add_i32 s10, s3, s4

.LBB0_226:
	v_readlane_b32 s4, v254, 1
	s_cmp_lt_i32 s4, 3
	s_cselect_b64 s[2:3], -1, 0
	s_and_b64 s[18:19], s[2:3], s[0:1]
	s_andn2_b64 vcc, exec, s[18:19]
	v_readlane_b32 s5, v254, 2
	v_readlane_b32 s6, v254, 3
	v_readlane_b32 s7, v254, 4
	s_cbranch_vccnz .LBB0_272
	s_mov_b32 s22, s88
	s_mov_b32 s21, s85
	s_mov_b32 s20, s91
	v_mbcnt_lo_u32_b32 v188, -1, 0
	v_mbcnt_hi_u32_b32 v188, -1, v188
	s_cmpk_gt_i32 s96, 0x3ff
	v_add_u32_e32 v224, s97, v188
	s_cbranch_scc1 .LBB0_260
	s_cmp_eq_u32 s101, 0
	s_cbranch_scc1 .LBB0_260
	v_bfe_u32 v2, v224, 3, 4
	v_lshlrev_b32_e32 v168, 4, v2
	v_mov_b32_e32 v169, 0
	v_lshl_add_u64 v[0:1], s[94:95], 0, v[168:169]
	s_mov_b64 s[0:1], 0x1a100000
	v_lshl_add_u64 v[170:171], v[0:1], 0, s[0:1]
	v_ashrrev_i32_e32 v0, 4, v224
	v_bfi_b32 v0, -8, v0, v188
	v_lshlrev_b32_e32 v189, 1, v0
	v_lshlrev_b32_e32 v7, 2, v0
	v_add_u32_e32 v0, 0x200, v224
	v_ashrrev_i32_e32 v0, 4, v0
	v_bfi_b32 v0, -8, v0, v188
	v_lshlrev_b32_e32 v190, 1, v0
	v_lshlrev_b32_e32 v8, 2, v0
	v_add_u32_e32 v0, 0x400, v224
	v_ashrrev_i32_e32 v0, 4, v0
	v_bfi_b32 v0, -8, v0, v188
	v_lshlrev_b32_e32 v191, 1, v0
	v_lshlrev_b32_e32 v9, 2, v0
	v_add_u32_e32 v0, 0x600, v224
	v_ashrrev_i32_e32 v0, 4, v0
	v_bfi_b32 v0, -8, v0, v188
	v_lshlrev_b32_e32 v192, 1, v0
	v_lshlrev_b32_e32 v10, 2, v0
	v_add_u32_e32 v0, 0x800, v224
	v_ashrrev_i32_e32 v0, 4, v0
	v_bfi_b32 v0, -8, v0, v188
	v_lshlrev_b32_e32 v193, 1, v0
	v_lshlrev_b32_e32 v11, 2, v0
	v_add_u32_e32 v0, 0xa00, v224
	v_ashrrev_i32_e32 v0, 4, v0
	v_bfi_b32 v0, -8, v0, v188
	v_lshlrev_b32_e32 v194, 1, v0
	v_lshlrev_b32_e32 v12, 2, v0
	v_add_u32_e32 v0, 0xc00, v224
	v_ashrrev_i32_e32 v0, 4, v0
	v_bfi_b32 v0, -8, v0, v188
	v_readlane_b32 s14, v254, 0
	s_movk_i32 s0, 0x1980
	v_lshlrev_b32_e32 v195, 1, v0
	v_lshlrev_b32_e32 v13, 2, v0
	v_ashrrev_i32_e32 v0, 4, v188
	s_lshl_b32 s33, s14, 4
	s_lshl_b32 s14, s14, 5
	v_mad_u32_u24 v6, v2, s0, 0
	v_and_b32_e32 v196, 15, v188
	v_lshlrev_b32_e32 v2, 3, v0
	v_and_b32_e32 v1, -16, v188
	s_add_i32 s14, s14, 0
	v_lshl_add_u32 v168, v196, 10, v1
	v_add_u32_e32 v14, s14, v2
	s_movk_i32 s14, 0x330
	v_mov_b32_e32 v1, 0xff00
	v_mad_u32_u24 v15, v196, s14, v1
	v_mov_b32_e32 v1, 0x13200
	v_mad_u32_u24 v16, v196, s14, v1
	v_mov_b32_e32 v1, 0x16500
	v_mad_u32_u24 v17, v196, s14, v1
	v_ashrrev_i32_e32 v1, 31, v0
	v_ashrrev_i32_e32 v3, 31, v2
	v_lshlrev_b32_e32 v197, 2, v0
	v_lshl_add_u64 v[4:5], s[94:95], 0, v[168:169]
	s_mov_b64 s[16:17], 0x18100000
	v_lshlrev_b64 v[0:1], 3, v[0:1]
	s_movk_i32 s0, 0xc80
	s_movk_i32 s2, 0xa80
	s_movk_i32 s4, 0x880
	s_movk_i32 s6, 0x680
	s_movk_i32 s8, 0x480
	s_movk_i32 s10, 0x280
	s_movk_i32 s12, 0x80
	v_lshl_add_u64 v[172:173], v[4:5], 0, s[16:17]
	v_lshl_add_u64 v[2:3], v[2:3], 1, s[94:95]
	s_mov_b64 s[16:17], 0x10100000
	v_sub_co_u32_e32 v176, vcc, 0, v0
	v_mbcnt_lo_u32_b32 v0, -1, 0
	s_mov_b32 s45, 0
	v_cmp_gt_i32_e64 s[0:1], s0, v224
	v_cmp_gt_i32_e64 s[2:3], s2, v224
	v_cmp_gt_i32_e64 s[4:5], s4, v224
	v_cmp_gt_i32_e64 s[6:7], s6, v224
	v_cmp_gt_i32_e64 s[8:9], s8, v224
	v_cmp_gt_i32_e64 s[10:11], s10, v224
	v_cmp_gt_i32_e64 s[12:13], s12, v224
	v_mad_u32_u24 v198, v196, s14, v14
	v_lshl_add_u64 v[174:175], v[2:3], 0, s[16:17]
	v_subb_co_u32_e32 v177, vcc, 0, v1, vcc
	s_mov_b32 s66, 0xffff
	v_add_u32_e32 v199, v6, v7
	s_mov_b32 s67, 0xffff0000
	v_add_u32_e32 v200, v6, v8
	v_add_u32_e32 v201, v6, v9
	v_add_u32_e32 v202, v6, v10
	v_add_u32_e32 v203, v6, v11
	v_add_u32_e32 v204, v6, v12
	v_add_u32_e32 v205, v6, v13
	s_mov_b32 s76, 0xc2fc0000
	s_mov_b32 s81, 0x3fb8aa3b
	s_movk_i32 s84, 0x81
	s_mov_b32 s85, 0xff61b1e6
	v_add_u32_e32 v206, v14, v16
	v_add_u32_e32 v207, v14, v17
	v_add_u32_e32 v208, v14, v15
	v_mov_b32_e32 v209, 0x7ff0
	v_mov_b32_e32 v210, 0x7fe0
	v_mov_b32_e32 v211, 0x42800000
	v_mov_b32_e32 v212, 0xf149f2ca
	v_mbcnt_hi_u32_b32 v213, -1, v0
	s_mov_b32 s88, s96

.LBB0_260:
	s_cmp_eq_u32 s101, 1
	s_cbranch_scc0 .Lmy_am_norm260
	s_mov_b32 s101, 2
	v_readlane_b32 s0, v255, 10
	v_readlane_b32 s1, v255, 11
	v_readlane_b32 s2, v255, 12
	v_readlane_b32 s3, v255, 13
	v_readlane_b32 s4, v255, 14
	v_readlane_b32 s5, v255, 15
	v_readlane_b32 s6, v255, 16
	v_readlane_b32 s7, v255, 17
	v_readlane_b32 s8, v255, 18
	v_readlane_b32 s9, v255, 19
	v_readlane_b32 s10, v255, 20
	v_readlane_b32 s11, v255, 21
	v_readlane_b32 s12, v255, 22
	v_readlane_b32 s13, v255, 23
	v_readlane_b32 s16, v255, 24
	v_readlane_b32 s17, v255, 25
	v_readlane_b32 s18, v255, 26
	v_readlane_b32 s19, v255, 27
	v_readlane_b32 s21, v255, 28
	v_readlane_b32 s33, v255, 29
	v_readlane_b32 s36, v255, 30
	v_readlane_b32 s37, v255, 31
	v_readlane_b32 s38, v255, 32
	v_readlane_b32 s40, v255, 33
	v_readlane_b32 s42, v255, 34
	v_readlane_b32 s43, v255, 35
	v_readlane_b32 s44, v255, 36
	v_readlane_b32 s45, v255, 37
	v_readlane_b32 s46, v255, 38
	v_readlane_b32 s47, v255, 39
	v_readlane_b32 s48, v255, 40
	v_readlane_b32 s49, v255, 41
	v_readlane_b32 s50, v255, 42
	v_readlane_b32 s51, v255, 43
	v_readlane_b32 s64, v255, 44
	v_readlane_b32 s85, v255, 45
	v_readlane_b32 s88, v255, 46
	v_readlane_b32 s91, v255, 47
	v_readlane_b32 s92, v255, 48
	s_mov_b64 s[0:1], -1
	s_branch .LBB0_326

.LBB0_326:
	s_cmp_eq_u32 s101, 0
	s_cbranch_scc0 .Lmy_am_norm326
	s_mov_b32 s101, 1
	v_writelane_b32 v255, s0, 10
	v_writelane_b32 v255, s1, 11
	v_writelane_b32 v255, s2, 12
	v_writelane_b32 v255, s3, 13
	v_writelane_b32 v255, s4, 14
	v_writelane_b32 v255, s5, 15
	v_writelane_b32 v255, s6, 16
	v_writelane_b32 v255, s7, 17
	v_writelane_b32 v255, s8, 18
	v_writelane_b32 v255, s9, 19
	v_writelane_b32 v255, s10, 20
	v_writelane_b32 v255, s11, 21
	v_writelane_b32 v255, s12, 22
	v_writelane_b32 v255, s13, 23
	v_writelane_b32 v255, s16, 24
	v_writelane_b32 v255, s17, 25
	v_writelane_b32 v255, s18, 26
	v_writelane_b32 v255, s19, 27
	v_writelane_b32 v255, s21, 28
	v_writelane_b32 v255, s33, 29
	v_writelane_b32 v255, s36, 30
	v_writelane_b32 v255, s37, 31
	v_writelane_b32 v255, s38, 32
	v_writelane_b32 v255, s40, 33
	v_writelane_b32 v255, s42, 34
	v_writelane_b32 v255, s43, 35
	v_writelane_b32 v255, s44, 36
	v_writelane_b32 v255, s45, 37
	v_writelane_b32 v255, s46, 38
	v_writelane_b32 v255, s47, 39
	v_writelane_b32 v255, s48, 40
	v_writelane_b32 v255, s49, 41
	v_writelane_b32 v255, s50, 42
	v_writelane_b32 v255, s51, 43
	v_writelane_b32 v255, s64, 44
	v_writelane_b32 v255, s85, 45
	v_writelane_b32 v255, s88, 46
	v_writelane_b32 v255, s91, 47
	v_writelane_b32 v255, s92, 48
	s_mov_b64 s[0:1], -1
	s_branch .LBB0_226
